# gate/up GEMM main loop: 16 per-iteration 64-bit VALU address adds removed, LDS-DMA loads use SGPR base + 32-bit voffset form
# speedup vs baseline: 1.0027x; 1.0018x over previous
.LBB0_1097:
	s_add_u32 s28, s26, 0xfffc0080
	s_addc_u32 s29, s27, -1
	s_add_i32 s59, 0, 0x10000
	s_cmp_eq_u32 s58, 12
	s_cselect_b32 s31, s19, s29
	s_cselect_b32 s30, s25, s28
	v_add_u32_e32 v140, s59, v143
	s_cselect_b32 s29, s17, s57
	s_cselect_b32 s28, s53, s56
	s_add_i32 s60, 0, 0x14000
	ds_read_b128 v[150:153], v140
	ds_read_b128 v[154:157], v140 offset:1024
	ds_read_b128 v[158:161], v140 offset:2048
	ds_read_b128 v[162:165], v140 offset:3072
	v_add_u32_e32 v140, s60, v143
	ds_read_b128 v[166:169], v140
	ds_read_b128 v[180:183], v140 offset:1024
	ds_read_b128 v[184:187], v140 offset:2048
	ds_read_b128 v[188:191], v140 offset:3072
	s_add_i32 m0, s41, 0xc000
	ds_read_b128 v[192:195], v149
	ds_read_b128 v[196:199], v149 offset:1024
	ds_read_b128 v[200:203], v149 offset:2048
	ds_read_b128 v[204:207], v149 offset:3072
	ds_read_b128 v[208:211], v149 offset:4096
	ds_read_b128 v[212:215], v149 offset:5120
	ds_read_b128 v[216:219], v149 offset:6144
	ds_read_b128 v[236:239], v149 offset:7168
	global_load_lds_dwordx4 v136, s[26:27]
	s_add_i32 m0, s41, 0xe000
	s_nop 0
	global_load_lds_dwordx4 v138, s[26:27]
	s_waitcnt vmcnt(8)
	s_waitcnt lgkmcnt(0)
	s_barrier
	s_setprio 1
	v_mfma_f32_16x16x32_bf16 v[126:129], v[150:153], v[192:195], v[126:129]
	v_mfma_f32_16x16x32_bf16 v[118:121], v[158:161], v[192:195], v[118:121]
	v_mfma_f32_16x16x32_bf16 v[110:113], v[150:153], v[200:203], v[110:113]
	v_mfma_f32_16x16x32_bf16 v[102:105], v[158:161], v[200:203], v[102:105]
	v_mfma_f32_16x16x32_bf16 v[94:97], v[150:153], v[208:211], v[94:97]
	v_mfma_f32_16x16x32_bf16 v[86:89], v[158:161], v[208:211], v[86:89]
	v_mfma_f32_16x16x32_bf16 v[78:81], v[150:153], v[216:219], v[78:81]
	v_mfma_f32_16x16x32_bf16 v[70:73], v[158:161], v[216:219], v[70:73]
	v_mfma_f32_16x16x32_bf16 v[126:129], v[154:157], v[196:199], v[126:129]
	v_mfma_f32_16x16x32_bf16 v[118:121], v[162:165], v[196:199], v[118:121]
	v_mfma_f32_16x16x32_bf16 v[110:113], v[154:157], v[204:207], v[110:113]
	v_mfma_f32_16x16x32_bf16 v[102:105], v[162:165], v[204:207], v[102:105]
	v_mfma_f32_16x16x32_bf16 v[94:97], v[154:157], v[212:215], v[94:97]
	v_mfma_f32_16x16x32_bf16 v[86:89], v[162:165], v[212:215], v[86:89]
	v_mfma_f32_16x16x32_bf16 v[78:81], v[154:157], v[236:239], v[78:81]
	v_mfma_f32_16x16x32_bf16 v[70:73], v[162:165], v[236:239], v[70:73]
	s_setprio 0
	s_setprio 1
	v_mfma_f32_16x16x32_bf16 v[122:125], v[166:169], v[192:195], v[122:125]
	v_mfma_f32_16x16x32_bf16 v[114:117], v[184:187], v[192:195], v[114:117]
	v_mfma_f32_16x16x32_bf16 v[106:109], v[166:169], v[200:203], v[106:109]
	v_mfma_f32_16x16x32_bf16 v[98:101], v[184:187], v[200:203], v[98:101]
	v_mfma_f32_16x16x32_bf16 v[90:93], v[166:169], v[208:211], v[90:93]
	v_mfma_f32_16x16x32_bf16 v[82:85], v[184:187], v[208:211], v[82:85]
	v_mfma_f32_16x16x32_bf16 v[74:77], v[166:169], v[216:219], v[74:77]
	v_mfma_f32_16x16x32_bf16 v[66:69], v[184:187], v[216:219], v[66:69]
	v_mfma_f32_16x16x32_bf16 v[122:125], v[180:183], v[196:199], v[122:125]
	v_mfma_f32_16x16x32_bf16 v[114:117], v[188:191], v[196:199], v[114:117]
	v_mfma_f32_16x16x32_bf16 v[106:109], v[180:183], v[204:207], v[106:109]
	v_mfma_f32_16x16x32_bf16 v[98:101], v[188:191], v[204:207], v[98:101]
	v_mfma_f32_16x16x32_bf16 v[90:93], v[180:183], v[212:215], v[90:93]
	v_mfma_f32_16x16x32_bf16 v[82:85], v[188:191], v[212:215], v[82:85]
	v_mfma_f32_16x16x32_bf16 v[74:77], v[180:183], v[236:239], v[74:77]
	v_mfma_f32_16x16x32_bf16 v[66:69], v[188:191], v[236:239], v[66:69]
	s_setprio 0
	s_barrier
	s_add_i32 s59, s59, s38
	s_mov_b32 m0, s59
	ds_read_b128 v[192:195], v149 offset:16384
	ds_read_b128 v[196:199], v149 offset:17408
	ds_read_b128 v[200:203], v149 offset:18432
	ds_read_b128 v[204:207], v149 offset:19456
	ds_read_b128 v[208:211], v149 offset:20480
	ds_read_b128 v[212:215], v149 offset:21504
	ds_read_b128 v[216:219], v149 offset:22528
	ds_read_b128 v[236:239], v149 offset:23552
	global_load_lds_dwordx4 v0, s[28:29]
	s_add_i32 m0, s59, 0x2000
	s_add_u32 s64, s28, 0x40000
	s_addc_u32 s65, s29, 0
	s_add_i32 s59, s60, s38
	global_load_lds_dwordx4 v130, s[28:29]
	s_mov_b32 m0, s59
	s_nop 0
	global_load_lds_dwordx4 v0, s[64:65]
	s_add_i32 m0, s59, 0x2000
	s_nop 0
	global_load_lds_dwordx4 v130, s[64:65]
	s_mov_b32 m0, s41
	s_add_u32 s100, s30, 0x80
	s_addc_u32 s101, s31, 0
	global_load_lds_dwordx4 v134, s[30:31]
	s_mov_b32 m0, s42
	s_nop 0
	global_load_lds_dwordx4 v132, s[30:31]
	s_waitcnt vmcnt(8)
	s_waitcnt lgkmcnt(0)
	s_barrier
	s_setprio 1
	v_mfma_f32_16x16x32_bf16 v[62:65], v[150:153], v[192:195], v[62:65]
	v_mfma_f32_16x16x32_bf16 v[54:57], v[158:161], v[192:195], v[54:57]
	v_mfma_f32_16x16x32_bf16 v[46:49], v[150:153], v[200:203], v[46:49]
	v_mfma_f32_16x16x32_bf16 v[38:41], v[158:161], v[200:203], v[38:41]
	v_mfma_f32_16x16x32_bf16 v[30:33], v[150:153], v[208:211], v[30:33]
	v_mfma_f32_16x16x32_bf16 v[22:25], v[158:161], v[208:211], v[22:25]
	v_mfma_f32_16x16x32_bf16 v[14:17], v[150:153], v[216:219], v[14:17]
	v_mfma_f32_16x16x32_bf16 v[6:9], v[158:161], v[216:219], v[6:9]
	v_mfma_f32_16x16x32_bf16 v[62:65], v[154:157], v[196:199], v[62:65]
	v_mfma_f32_16x16x32_bf16 v[54:57], v[162:165], v[196:199], v[54:57]
	v_mfma_f32_16x16x32_bf16 v[46:49], v[154:157], v[204:207], v[46:49]
	v_mfma_f32_16x16x32_bf16 v[38:41], v[162:165], v[204:207], v[38:41]
	v_mfma_f32_16x16x32_bf16 v[30:33], v[154:157], v[212:215], v[30:33]
	v_mfma_f32_16x16x32_bf16 v[22:25], v[162:165], v[212:215], v[22:25]
	v_mfma_f32_16x16x32_bf16 v[14:17], v[154:157], v[236:239], v[14:17]
	v_mfma_f32_16x16x32_bf16 v[6:9], v[162:165], v[236:239], v[6:9]
	s_setprio 0
	s_setprio 1
	v_mfma_f32_16x16x32_bf16 v[58:61], v[166:169], v[192:195], v[58:61]
	v_mfma_f32_16x16x32_bf16 v[50:53], v[184:187], v[192:195], v[50:53]
	v_mfma_f32_16x16x32_bf16 v[42:45], v[166:169], v[200:203], v[42:45]
	v_mfma_f32_16x16x32_bf16 v[34:37], v[184:187], v[200:203], v[34:37]
	v_mfma_f32_16x16x32_bf16 v[26:29], v[166:169], v[208:211], v[26:29]
	v_mfma_f32_16x16x32_bf16 v[18:21], v[184:187], v[208:211], v[18:21]
	v_mfma_f32_16x16x32_bf16 v[10:13], v[166:169], v[216:219], v[10:13]
	v_mfma_f32_16x16x32_bf16 v[2:5], v[184:187], v[216:219], v[2:5]
	v_mfma_f32_16x16x32_bf16 v[58:61], v[180:183], v[196:199], v[58:61]
	v_mfma_f32_16x16x32_bf16 v[50:53], v[188:191], v[196:199], v[50:53]
	v_mfma_f32_16x16x32_bf16 v[42:45], v[180:183], v[204:207], v[42:45]
	v_mfma_f32_16x16x32_bf16 v[34:37], v[188:191], v[204:207], v[34:37]
	v_mfma_f32_16x16x32_bf16 v[26:29], v[180:183], v[212:215], v[26:29]
	v_mfma_f32_16x16x32_bf16 v[18:21], v[188:191], v[212:215], v[18:21]
	v_mfma_f32_16x16x32_bf16 v[10:13], v[180:183], v[236:239], v[10:13]
	v_mfma_f32_16x16x32_bf16 v[2:5], v[188:191], v[236:239], v[2:5]
	s_setprio 0
	s_barrier
	s_add_i32 s59, 0, 0x18000
	s_add_i32 s60, 0, 0x1c000
	v_add_u32_e32 v162, s59, v143
	v_add_u32_e32 v188, s60, v143
	ds_read_b128 v[150:153], v162
	ds_read_b128 v[154:157], v162 offset:1024
	ds_read_b128 v[158:161], v162 offset:2048
	ds_read_b128 v[162:165], v162 offset:3072
	ds_read_b128 v[166:169], v188
	ds_read_b128 v[180:183], v188 offset:1024
	ds_read_b128 v[184:187], v188 offset:2048
	ds_read_b128 v[188:191], v188 offset:3072
	s_add_u32 s30, s30, 0x40000
	s_addc_u32 s31, s31, 0
	s_mov_b32 m0, s43
	ds_read_b128 v[192:195], v149 offset:32768
	ds_read_b128 v[196:199], v149 offset:33792
	ds_read_b128 v[200:203], v149 offset:34816
	ds_read_b128 v[204:207], v149 offset:35840
	ds_read_b128 v[208:211], v149 offset:36864
	ds_read_b128 v[212:215], v149 offset:37888
	ds_read_b128 v[216:219], v149 offset:38912
	ds_read_b128 v[236:239], v149 offset:39936
	global_load_lds_dwordx4 v134, s[30:31]
	s_mov_b32 m0, s46
	s_nop 0
	global_load_lds_dwordx4 v132, s[30:31]
	s_waitcnt vmcnt(8)
	s_waitcnt lgkmcnt(0)
	s_barrier
	s_setprio 1
	v_mfma_f32_16x16x32_bf16 v[126:129], v[150:153], v[192:195], v[126:129]
	v_mfma_f32_16x16x32_bf16 v[118:121], v[158:161], v[192:195], v[118:121]
	v_mfma_f32_16x16x32_bf16 v[110:113], v[150:153], v[200:203], v[110:113]
	v_mfma_f32_16x16x32_bf16 v[102:105], v[158:161], v[200:203], v[102:105]
	v_mfma_f32_16x16x32_bf16 v[94:97], v[150:153], v[208:211], v[94:97]
	v_mfma_f32_16x16x32_bf16 v[86:89], v[158:161], v[208:211], v[86:89]
	v_mfma_f32_16x16x32_bf16 v[78:81], v[150:153], v[216:219], v[78:81]
	v_mfma_f32_16x16x32_bf16 v[70:73], v[158:161], v[216:219], v[70:73]
	v_mfma_f32_16x16x32_bf16 v[126:129], v[154:157], v[196:199], v[126:129]
	v_mfma_f32_16x16x32_bf16 v[118:121], v[162:165], v[196:199], v[118:121]
	v_mfma_f32_16x16x32_bf16 v[110:113], v[154:157], v[204:207], v[110:113]
	v_mfma_f32_16x16x32_bf16 v[102:105], v[162:165], v[204:207], v[102:105]
	v_mfma_f32_16x16x32_bf16 v[94:97], v[154:157], v[212:215], v[94:97]
	v_mfma_f32_16x16x32_bf16 v[86:89], v[162:165], v[212:215], v[86:89]
	v_mfma_f32_16x16x32_bf16 v[78:81], v[154:157], v[236:239], v[78:81]
	v_mfma_f32_16x16x32_bf16 v[70:73], v[162:165], v[236:239], v[70:73]
	s_setprio 0
	s_setprio 1
	v_mfma_f32_16x16x32_bf16 v[122:125], v[166:169], v[192:195], v[122:125]
	v_mfma_f32_16x16x32_bf16 v[114:117], v[184:187], v[192:195], v[114:117]
	v_mfma_f32_16x16x32_bf16 v[106:109], v[166:169], v[200:203], v[106:109]
	v_mfma_f32_16x16x32_bf16 v[98:101], v[184:187], v[200:203], v[98:101]
	v_mfma_f32_16x16x32_bf16 v[90:93], v[166:169], v[208:211], v[90:93]
	v_mfma_f32_16x16x32_bf16 v[82:85], v[184:187], v[208:211], v[82:85]
	v_mfma_f32_16x16x32_bf16 v[74:77], v[166:169], v[216:219], v[74:77]
	v_mfma_f32_16x16x32_bf16 v[66:69], v[184:187], v[216:219], v[66:69]
	v_mfma_f32_16x16x32_bf16 v[122:125], v[180:183], v[196:199], v[122:125]
	v_mfma_f32_16x16x32_bf16 v[114:117], v[188:191], v[196:199], v[114:117]
	v_mfma_f32_16x16x32_bf16 v[106:109], v[180:183], v[204:207], v[106:109]
	v_mfma_f32_16x16x32_bf16 v[98:101], v[188:191], v[204:207], v[98:101]
	v_mfma_f32_16x16x32_bf16 v[90:93], v[180:183], v[212:215], v[90:93]
	v_mfma_f32_16x16x32_bf16 v[82:85], v[188:191], v[212:215], v[82:85]
	v_mfma_f32_16x16x32_bf16 v[74:77], v[180:183], v[236:239], v[74:77]
	v_mfma_f32_16x16x32_bf16 v[66:69], v[188:191], v[236:239], v[66:69]
	s_setprio 0
	s_barrier
	s_add_i32 s30, s59, s38
	s_add_u32 s64, s28, 0x80
	s_addc_u32 s65, s29, 0
	s_mov_b32 m0, s30
	ds_read_b128 v[192:195], v149 offset:49152
	ds_read_b128 v[196:199], v149 offset:50176
	ds_read_b128 v[200:203], v149 offset:51200
	ds_read_b128 v[204:207], v149 offset:52224
	ds_read_b128 v[208:211], v149 offset:53248
	ds_read_b128 v[212:215], v149 offset:54272
	ds_read_b128 v[216:219], v149 offset:55296
	ds_read_b128 v[236:239], v149 offset:56320
	global_load_lds_dwordx4 v0, s[64:65]
	s_add_i32 m0, s30, 0x2000
	s_add_u32 s28, s28, 0x40080
	s_addc_u32 s29, s29, 0
	s_add_i32 s30, s60, s38
	global_load_lds_dwordx4 v130, s[64:65]
	s_mov_b32 m0, s30
	s_nop 0
	global_load_lds_dwordx4 v0, s[28:29]
	s_add_i32 m0, s30, 0x2000
	s_nop 0
	global_load_lds_dwordx4 v130, s[28:29]
	s_mov_b32 m0, s47
	s_nop 0
	global_load_lds_dwordx4 v134, s[100:101]
	s_mov_b32 m0, s50
	s_nop 0
	global_load_lds_dwordx4 v132, s[100:101]
	s_waitcnt vmcnt(8)
	s_waitcnt lgkmcnt(0)
	s_barrier
	s_setprio 1
	v_mfma_f32_16x16x32_bf16 v[62:65], v[150:153], v[192:195], v[62:65]
	v_mfma_f32_16x16x32_bf16 v[54:57], v[158:161], v[192:195], v[54:57]
	v_mfma_f32_16x16x32_bf16 v[46:49], v[150:153], v[200:203], v[46:49]
	v_mfma_f32_16x16x32_bf16 v[38:41], v[158:161], v[200:203], v[38:41]
	v_mfma_f32_16x16x32_bf16 v[30:33], v[150:153], v[208:211], v[30:33]
	v_mfma_f32_16x16x32_bf16 v[22:25], v[158:161], v[208:211], v[22:25]
	v_mfma_f32_16x16x32_bf16 v[14:17], v[150:153], v[216:219], v[14:17]
	v_mfma_f32_16x16x32_bf16 v[6:9], v[158:161], v[216:219], v[6:9]
	v_mfma_f32_16x16x32_bf16 v[62:65], v[154:157], v[196:199], v[62:65]
	v_mfma_f32_16x16x32_bf16 v[54:57], v[162:165], v[196:199], v[54:57]
	v_mfma_f32_16x16x32_bf16 v[46:49], v[154:157], v[204:207], v[46:49]
	v_mfma_f32_16x16x32_bf16 v[38:41], v[162:165], v[204:207], v[38:41]
	v_mfma_f32_16x16x32_bf16 v[30:33], v[154:157], v[212:215], v[30:33]
	v_mfma_f32_16x16x32_bf16 v[22:25], v[162:165], v[212:215], v[22:25]
	v_mfma_f32_16x16x32_bf16 v[14:17], v[154:157], v[236:239], v[14:17]
	v_mfma_f32_16x16x32_bf16 v[6:9], v[162:165], v[236:239], v[6:9]
	s_setprio 0
	s_setprio 1
	v_mfma_f32_16x16x32_bf16 v[58:61], v[166:169], v[192:195], v[58:61]
	v_mfma_f32_16x16x32_bf16 v[50:53], v[184:187], v[192:195], v[50:53]
	v_mfma_f32_16x16x32_bf16 v[42:45], v[166:169], v[200:203], v[42:45]
	v_mfma_f32_16x16x32_bf16 v[34:37], v[184:187], v[200:203], v[34:37]
	v_mfma_f32_16x16x32_bf16 v[26:29], v[166:169], v[208:211], v[26:29]
	v_mfma_f32_16x16x32_bf16 v[18:21], v[184:187], v[208:211], v[18:21]
	v_mfma_f32_16x16x32_bf16 v[10:13], v[166:169], v[216:219], v[10:13]
	v_mfma_f32_16x16x32_bf16 v[2:5], v[184:187], v[216:219], v[2:5]
	v_mfma_f32_16x16x32_bf16 v[58:61], v[180:183], v[196:199], v[58:61]
	v_mfma_f32_16x16x32_bf16 v[50:53], v[188:191], v[196:199], v[50:53]
	v_mfma_f32_16x16x32_bf16 v[42:45], v[180:183], v[204:207], v[42:45]
	v_mfma_f32_16x16x32_bf16 v[34:37], v[188:191], v[204:207], v[34:37]
	v_mfma_f32_16x16x32_bf16 v[26:29], v[180:183], v[212:215], v[26:29]
	v_mfma_f32_16x16x32_bf16 v[18:21], v[188:191], v[212:215], v[18:21]
	v_mfma_f32_16x16x32_bf16 v[10:13], v[180:183], v[236:239], v[10:13]
	v_mfma_f32_16x16x32_bf16 v[2:5], v[188:191], v[236:239], v[2:5]
	s_setprio 0
	s_barrier
	s_add_i32 s58, s58, 2
	s_add_u32 s26, s26, 0x100
	s_addc_u32 s27, s27, 0
	s_add_u32 s56, s56, 0x100
	s_addc_u32 s57, s57, 0
	s_cmp_gt_u32 s58, 13
	s_cbranch_scc0 .LBB0_1097
	s_and_b64 vcc, exec, s[14:15]
	s_cbranch_vccz .LBB0_1100
	s_barrier
